# v31 + nt also on the P3 QA/KA stage loads
# speedup vs baseline: 1.0159x; 1.0030x over previous
.Lev_skip_a:
	s_add_i32 s34, s49, 3
	v_sub_u32_e64 v32, 60, s44 clamp
	s_and_b64 s[20:21], exec, s[38:39]
	v_readfirstlane_b32 s20, v32
	s_cselect_b32 s66, s34, s20
	s_lshl_b32 s34, s66, 13
	s_lshl_b32 s67, s66, 14
	s_add_u32 s20, s43, s67
	s_addc_u32 s21, s63, 0
	v_lshl_add_u64 v[36:37], s[20:21], 0, v[120:121]
	global_load_dwordx4 v[32:35], v120, s[20:21] nt
	v_add_co_u32_e64 v36, s[20:21], s60, v36
	v_lshl_add_u64 v[48:49], v[146:147], 0, s[34:35]
	s_nop 0
	v_addc_co_u32_e64 v37, s[20:21], 0, v37, s[20:21]
	s_add_u32 s20, s64, s67
	s_addc_u32 s21, s65, 0
	v_lshl_add_u64 v[44:45], s[20:21], 0, v[120:121]
	global_load_dwordx4 v[36:39], v[36:37], off nt
	s_lshl_b32 s34, s66, 10
	global_load_dwordx4 v[40:43], v120, s[20:21] nt
	v_add_co_u32_e64 v44, s[20:21], s60, v44
	v_lshl_add_u64 v[52:53], v[148:149], 0, s[34:35]
	s_nop 0
	v_addc_co_u32_e64 v45, s[20:21], 0, v45, s[20:21]
	s_lshl_b32 s20, s49, 1
	s_add_i32 s34, s20, 4
	s_waitcnt vmcnt(15)
	v_mov_b32_e32 v214, v64
	v_mov_b32_e32 v215, v65
	v_mov_b32_e32 v216, v66
	v_mov_b32_e32 v217, v67
	v_lshl_add_u64 v[64:65], v[144:145], 0, s[34:35]
	s_add_i32 s34, 0, 0x1e400
	v_mov_b32_e32 v198, v56
	v_mov_b32_e32 v199, v57
	v_mov_b32_e32 v200, v58
	v_mov_b32_e32 v201, v59
	v_mov_b32_e32 v202, v60
	v_mov_b32_e32 v203, v61
	v_mov_b32_e32 v204, v62
	v_mov_b32_e32 v205, v63
	s_waitcnt vmcnt(14)
	v_mov_b32_e32 v242, v68
	v_mov_b32_e32 v243, v69
	v_mov_b32_e32 v244, v70
	v_mov_b32_e32 v245, v71
	v_add_u32_e32 v116, s34, v143
	ds_read_b128 v[190:193], v116
	v_and_b32_e32 v66, 0xfff, v64
	v_cmp_ne_u32_e64 s[20:21], 0, v66
	v_add_u32_e32 v185, 0, v143
	v_add_u32_e32 v116, 0x1e600, v185
	s_waitcnt lgkmcnt(0)
	v_pk_mul_f32 v[192:193], v[98:99], v[192:193]
	v_pk_mul_f32 v[190:191], v[96:97], v[190:191]
	v_pk_mul_f32 v[98:99], v[102:103], v[192:193]
	v_pk_mul_f32 v[96:97], v[100:101], v[190:191]
	v_cndmask_b32_e64 v56, 0, 1, s[20:21]
	v_cvt_pk_bf16_f32 v100, v96, v97
	v_cvt_pk_bf16_f32 v101, v98, v99
	v_sub_co_u32_e64 v56, s[20:21], v64, v56
	ds_read_b128 v[116:119], v116
	ds_write_b64 v182, v[100:101]
	v_pk_mul_f32 v[100:101], v[104:105], v[190:191]
	v_pk_mul_f32 v[102:103], v[106:107], v[192:193]
	v_subbrev_co_u32_e64 v57, s[20:21], 0, v65, s[20:21]
	v_cvt_pk_bf16_f32 v104, v100, v101
	v_cvt_pk_bf16_f32 v105, v102, v103
	v_cmp_ne_u32_e64 s[20:21], s62, v66
	ds_write_b64 v182, v[104:105] offset:4352
	v_pk_mul_f32 v[104:105], v[108:109], v[190:191]
	v_pk_mul_f32 v[106:107], v[110:111], v[192:193]
	v_cndmask_b32_e64 v66, 0, 1, s[20:21]
	v_mov_b32_e32 v67, s35
	v_cvt_pk_bf16_f32 v108, v104, v105
	v_cvt_pk_bf16_f32 v109, v106, v107
	v_lshlrev_b64 v[68:69], 11, v[64:65]
	v_lshl_add_u64 v[64:65], v[64:65], 0, v[66:67]
	ds_write_b64 v182, v[108:109] offset:8704
	v_pk_mul_f32 v[108:109], v[112:113], v[190:191]
	v_pk_mul_f32 v[110:111], v[114:115], v[192:193]
	v_lshlrev_b64 v[56:57], 11, v[56:57]
	v_lshlrev_b64 v[64:65], 11, v[64:65]
	v_cvt_pk_bf16_f32 v112, v108, v109
	v_cvt_pk_bf16_f32 v113, v110, v111
	v_lshl_add_u64 v[56:57], v[134:135], 0, v[56:57]
	v_lshl_add_u64 v[60:61], v[134:135], 0, v[68:69]
	v_lshl_add_u64 v[64:65], v[134:135], 0, v[64:65]
	v_lshl_add_u64 v[68:69], v[136:137], 0, v[68:69]
	ds_write_b64 v182, v[112:113] offset:13056
	global_load_dwordx4 v[44:47], v[44:45], off nt
	global_load_dwordx4 v[48:51], v[48:49], off nt
	global_load_dwordx4 v[52:55], v[52:53], off
	global_load_dwordx4 v[56:59], v[56:57], off
	s_lshl_b32 s48, s48, 6
	global_load_dwordx4 v[60:63], v[60:61], off
	s_nop 0
	global_load_dwordx4 v[64:67], v[64:65], off
	s_nop 0
	global_load_dwordx4 v[68:71], v[68:69], off nt
	s_waitcnt lgkmcnt(0)
	s_barrier
	ds_read_b128 v[218:221], v170 offset:61440
	ds_read_b128 v[222:225], v171 offset:44032
	ds_read_b128 v[226:229], v172 offset:44032
	ds_read_b128 v[230:233], v170 offset:61504
	ds_read_b128 v[234:237], v171 offset:44096
	ds_read_b128 v[238:241], v172 offset:44096
	v_and_b32_e32 v250, 0xfff, v184
	v_cmp_ne_u32_e64 s[20:21], 0, v250
	v_add_u32_e32 v184, 4, v184
	s_nop 0
	v_cndmask_b32_e64 v198, 0, v198, s[20:21]
	v_cndmask_b32_e64 v199, 0, v199, s[20:21]
	v_cndmask_b32_e64 v200, 0, v200, s[20:21]
	v_cndmask_b32_e64 v201, 0, v201, s[20:21]
	v_cmp_ne_u32_e64 s[20:21], s62, v250
	v_lshlrev_b32_e32 v246, 16, v202
	v_and_b32_e32 v247, 0xffff0000, v202
	v_cndmask_b32_e64 v214, 0, v214, s[20:21]
	v_cndmask_b32_e64 v215, 0, v215, s[20:21]
	v_cndmask_b32_e64 v216, 0, v216, s[20:21]
	v_cndmask_b32_e64 v217, 0, v217, s[20:21]
	v_pk_mul_f32 v[246:247], v[8:9], v[246:247]
	v_lshlrev_b32_e32 v248, 16, v198
	v_and_b32_e32 v249, 0xffff0000, v198
	v_pk_fma_f32 v[246:247], v[0:1], v[248:249], v[246:247]
	v_lshlrev_b32_e32 v248, 16, v214
	v_and_b32_e32 v249, 0xffff0000, v214
	v_pk_fma_f32 v[246:247], v[16:17], v[248:249], v[246:247]
	v_pk_add_f32 v[246:247], v[24:25], v[246:247]
	v_lshlrev_b32_e32 v248, 16, v242
	v_and_b32_e32 v249, 0xffff0000, v242
	v_pk_mul_f32 v[246:247], v[246:247], v[248:249]
	v_cvt_pk_bf16_f32 v198, v246, v247
	v_lshlrev_b32_e32 v246, 16, v203
	v_and_b32_e32 v247, 0xffff0000, v203
	v_pk_mul_f32 v[246:247], v[10:11], v[246:247]
	v_lshlrev_b32_e32 v248, 16, v199
	v_and_b32_e32 v249, 0xffff0000, v199
	v_pk_fma_f32 v[246:247], v[2:3], v[248:249], v[246:247]
	v_lshlrev_b32_e32 v248, 16, v215
	v_and_b32_e32 v249, 0xffff0000, v215
	v_pk_fma_f32 v[246:247], v[18:19], v[248:249], v[246:247]
	v_pk_add_f32 v[246:247], v[26:27], v[246:247]
	v_lshlrev_b32_e32 v248, 16, v243
	v_and_b32_e32 v249, 0xffff0000, v243
	v_pk_mul_f32 v[246:247], v[246:247], v[248:249]
	v_cvt_pk_bf16_f32 v199, v246, v247
	v_lshlrev_b32_e32 v246, 16, v204
	v_and_b32_e32 v247, 0xffff0000, v204
	v_pk_mul_f32 v[246:247], v[12:13], v[246:247]
	v_lshlrev_b32_e32 v248, 16, v200
	v_and_b32_e32 v249, 0xffff0000, v200
	v_pk_fma_f32 v[246:247], v[4:5], v[248:249], v[246:247]
	v_lshlrev_b32_e32 v248, 16, v216
	v_and_b32_e32 v249, 0xffff0000, v216
	v_pk_fma_f32 v[246:247], v[20:21], v[248:249], v[246:247]
	v_pk_add_f32 v[246:247], v[28:29], v[246:247]
	v_lshlrev_b32_e32 v248, 16, v244
	v_and_b32_e32 v249, 0xffff0000, v244
	v_pk_mul_f32 v[246:247], v[246:247], v[248:249]
	v_cvt_pk_bf16_f32 v200, v246, v247
	v_lshlrev_b32_e32 v246, 16, v205
	v_and_b32_e32 v247, 0xffff0000, v205
	v_pk_mul_f32 v[246:247], v[14:15], v[246:247]
	v_lshlrev_b32_e32 v248, 16, v201
	v_and_b32_e32 v249, 0xffff0000, v201
	v_pk_fma_f32 v[246:247], v[6:7], v[248:249], v[246:247]
	v_lshlrev_b32_e32 v248, 16, v217
	v_and_b32_e32 v249, 0xffff0000, v217
	v_pk_fma_f32 v[246:247], v[22:23], v[248:249], v[246:247]
	v_pk_add_f32 v[246:247], v[30:31], v[246:247]
	v_lshlrev_b32_e32 v248, 16, v245
	v_and_b32_e32 v249, 0xffff0000, v245
	v_pk_mul_f32 v[246:247], v[246:247], v[248:249]
	v_cvt_pk_bf16_f32 v201, v246, v247
	global_store_dwordx4 v[152:153], v[198:201], off
	ds_read_b128 v[242:245], v170 offset:61568
	ds_read_b128 v[246:249], v171 offset:44160
	ds_read_b128 v[250:253], v172 offset:44160
	s_waitcnt lgkmcnt(6)
	v_mfma_f32_16x16x32_bf16 v[190:193], v[218:221], v[222:225], 0
	v_mfma_f32_16x16x32_bf16 v[194:197], v[218:221], v[226:229], 0
	ds_read_b128 v[218:221], v170 offset:61632
	ds_read_b128 v[222:225], v171 offset:44224
	ds_read_b128 v[226:229], v172 offset:44224
	s_waitcnt lgkmcnt(6)
	v_mfma_f32_16x16x32_bf16 v[190:193], v[230:233], v[234:237], v[190:193]
	v_mfma_f32_16x16x32_bf16 v[194:197], v[230:233], v[238:241], v[194:197]
	ds_read_b64_tr_b16 v[230:231], v206 offset:34816
	ds_read_b64_tr_b16 v[232:233], v206 offset:35392
	ds_read_b128 v[234:237], v208
	ds_read_b128 v[238:241], v209
	s_waitcnt lgkmcnt(7)
	v_mfma_f32_16x16x32_bf16 v[190:193], v[242:245], v[246:249], v[190:193]
	v_mfma_f32_16x16x32_bf16 v[194:197], v[242:245], v[250:253], v[194:197]
	ds_read_b64_tr_b16 v[242:243], v206 offset:39424
	ds_read_b64_tr_b16 v[244:245], v206 offset:40000
	ds_read_b128 v[246:249], v208 offset:64
	ds_read_b128 v[250:253], v209 offset:64
	s_waitcnt lgkmcnt(8)
	v_mfma_f32_16x16x32_bf16 v[190:193], v[218:221], v[222:225], v[190:193]
	v_mfma_f32_16x16x32_bf16 v[194:197], v[218:221], v[226:229], v[194:197]
	ds_read_b128 v[218:221], v183
	ds_read_b128 v[222:225], v171
	ds_read_b128 v[226:229], v172
	s_waitcnt lgkmcnt(7)
	v_mfma_f32_16x16x32_bf16 v[198:201], v[230:233], v[234:237], 0
	v_mfma_f32_16x16x32_bf16 v[202:205], v[230:233], v[238:241], 0
	ds_read_b128 v[230:233], v183 offset:64
	ds_read_b128 v[234:237], v171 offset:64
	ds_read_b128 v[238:241], v172 offset:64
	s_waitcnt lgkmcnt(6)
	v_mfma_f32_16x16x32_bf16 v[198:201], v[242:245], v[246:249], v[198:201]
	v_mfma_f32_16x16x32_bf16 v[202:205], v[242:245], v[250:253], v[202:205]
	ds_read_b128 v[242:245], v183 offset:128
	ds_read_b128 v[246:249], v171 offset:128
	ds_read_b128 v[250:253], v172 offset:128
	v_cndmask_b32_e32 v190, 0, v190, vcc
	v_cndmask_b32_e64 v191, 0, v191, s[6:7]
	v_cndmask_b32_e64 v192, 0, v192, s[8:9]
	v_cndmask_b32_e64 v193, 0, v193, s[10:11]
	v_cvt_pk_bf16_f32 v190, v190, v191
	v_cvt_pk_bf16_f32 v191, v192, v193
	v_cndmask_b32_e64 v194, 0, v194, s[12:13]
	v_cndmask_b32_e64 v195, 0, v195, s[14:15]
	v_cndmask_b32_e64 v196, 0, v196, s[16:17]
	v_cndmask_b32_e64 v197, 0, v197, s[18:19]
	v_cvt_pk_bf16_f32 v194, v194, v195
	v_cvt_pk_bf16_f32 v195, v196, v197
	ds_write_b64 v212, v[190:191]
	ds_write_b64 v213, v[194:195]
	s_waitcnt lgkmcnt(8)
	v_mfma_f32_16x16x32_bf16 v[198:201], v[218:221], v[222:225], v[198:201]
	v_mfma_f32_16x16x32_bf16 v[202:205], v[218:221], v[226:229], v[202:205]
	ds_read_b64_tr_b16 v[190:191], v178 offset:17408
	ds_read_b64_tr_b16 v[192:193], v178 offset:18496
	ds_read_b64_tr_b16 v[194:195], v178 offset:26112
	ds_read_b64_tr_b16 v[196:197], v178 offset:27200
	s_waitcnt lgkmcnt(9)
	v_mfma_f32_16x16x32_bf16 v[198:201], v[230:233], v[234:237], v[198:201]
	v_mfma_f32_16x16x32_bf16 v[202:205], v[230:233], v[238:241], v[202:205]
	ds_read_b128 v[230:233], v183 offset:192
	ds_read_b128 v[234:237], v171 offset:192
	ds_read_b128 v[238:241], v172 offset:192
	s_waitcnt lgkmcnt(9)
	v_mfma_f32_16x16x32_bf16 v[198:201], v[242:245], v[246:249], v[198:201]
	v_mfma_f32_16x16x32_bf16 v[202:205], v[242:245], v[250:253], v[202:205]
	ds_read_b64_tr_b16 v[242:243], v161 offset:34816
	ds_read_b64_tr_b16 v[244:245], v161 offset:35392
	ds_read_b64_tr_b16 v[246:247], v161 offset:34848
	ds_read_b64_tr_b16 v[248:249], v161 offset:35424
	s_waitcnt lgkmcnt(7)
	ds_read_b64_tr_b16 v[218:219], v161 offset:34880
	ds_read_b64_tr_b16 v[220:221], v161 offset:35456
	ds_read_b64_tr_b16 v[222:223], v161 offset:34912
	ds_read_b64_tr_b16 v[224:225], v161 offset:35488
	s_waitcnt lgkmcnt(8)
	v_mfma_f32_16x16x32_bf16 v[198:201], v[230:233], v[234:237], v[198:201]
	v_mfma_f32_16x16x32_bf16 v[202:205], v[230:233], v[238:241], v[202:205]
	ds_read_b64_tr_b16 v[230:231], v161 offset:39424
	ds_read_b64_tr_b16 v[232:233], v161 offset:40000
	ds_read_b64_tr_b16 v[234:235], v161 offset:39456
	ds_read_b64_tr_b16 v[236:237], v161 offset:40032
	s_waitcnt lgkmcnt(8)
	v_mfma_f32_16x16x32_bf16 v[96:99], v[190:193], v[242:245], v[96:99]
	v_mfma_f32_16x16x32_bf16 v[100:103], v[190:193], v[246:249], v[100:103]
	ds_read_b64_tr_b16 v[242:243], v161 offset:39488
	ds_read_b64_tr_b16 v[244:245], v161 offset:40064
	ds_read_b64_tr_b16 v[246:247], v161 offset:39520
	ds_read_b64_tr_b16 v[248:249], v161 offset:40096
	v_cvt_pk_bf16_f32 v198, v198, v199
	v_cvt_pk_bf16_f32 v199, v200, v201
	v_add_u32_e32 v254, s48, v173
	v_mad_u64_u32 v[254:255], s[20:21], v254, s42, 0
	v_lshl_add_u64 v[254:255], v[254:255], 1, v[150:151]
	v_cvt_pk_bf16_f32 v202, v202, v203
	v_cvt_pk_bf16_f32 v203, v204, v205
	global_store_dwordx2 v[254:255], v[198:199], off
	v_add_u32_e32 v254, s48, v179
	v_mad_u64_u32 v[254:255], s[20:21], v254, s42, 0
	v_lshl_add_u64 v[254:255], v[254:255], 1, v[150:151]
	global_store_dwordx2 v[254:255], v[202:203], off
	s_waitcnt lgkmcnt(8)
	v_mfma_f32_16x16x32_bf16 v[104:107], v[190:193], v[218:221], v[104:107]
	v_mfma_f32_16x16x32_bf16 v[214:217], v[190:193], v[222:225], v[108:111]
	s_waitcnt lgkmcnt(4)
	v_mfma_f32_16x16x32_bf16 v[112:115], v[194:197], v[230:233], v[96:99]
	v_mfma_f32_16x16x32_bf16 v[108:111], v[194:197], v[234:237], v[100:103]
	s_waitcnt lgkmcnt(0)
	v_mfma_f32_16x16x32_bf16 v[104:107], v[194:197], v[242:245], v[104:107]
	v_mfma_f32_16x16x32_bf16 v[100:103], v[194:197], v[246:249], v[214:217]
	s_min_u32 s20, s44, 59
	s_waitcnt lgkmcnt(0)
	s_barrier
	s_waitcnt vmcnt(20)
	ds_write_b128 v168, v[72:75]
	s_waitcnt vmcnt(19)
	ds_write_b128 v168, v[80:83] offset:8704
	s_waitcnt vmcnt(18)
	ds_write_b128 v168, v[76:79] offset:17408
	s_waitcnt vmcnt(17)
	ds_write_b128 v168, v[84:87] offset:26112
	s_waitcnt vmcnt(16)
	ds_write_b128 v169, v[88:91] offset:34816
	v_add_u32_e32 v72, s34, v154
	s_add_i32 s34, s20, 4
	s_waitcnt vmcnt(15)
	s_cmp_lg_u32 s69, 0
	s_cbranch_scc1 .Lev_skip_b
	ds_write_b128 v72, v[92:95]
.Lev_skip_b:
	v_sub_u32_e64 v72, 59, s44 clamp
	s_and_b64 s[20:21], exec, s[38:39]
	v_readfirstlane_b32 s20, v72
	s_cselect_b32 s48, s34, s20
	v_add_u32_e32 v96, s61, v143
	s_lshl_b32 s34, s48, 13
	s_lshl_b32 s49, s48, 14
	ds_read_b128 v[186:189], v96
	s_add_u32 s20, s43, s49
	s_addc_u32 s21, s63, 0
	v_lshl_add_u64 v[76:77], s[20:21], 0, v[120:121]
	global_load_dwordx4 v[72:75], v120, s[20:21] nt
	v_add_co_u32_e64 v76, s[20:21], s60, v76
	s_waitcnt lgkmcnt(0)
	v_pk_mul_f32 v[118:119], v[118:119], v[188:189]
	v_addc_co_u32_e64 v77, s[20:21], 0, v77, s[20:21]
	v_pk_mul_f32 v[116:117], v[116:117], v[186:187]
	s_add_u32 s20, s64, s49
	v_pk_mul_f32 v[114:115], v[114:115], v[118:119]
	v_pk_mul_f32 v[112:113], v[112:113], v[116:117]
	s_addc_u32 s21, s65, 0
	v_add_u32_e32 v96, 0x1ea00, v185
	v_cvt_pk_bf16_f32 v186, v112, v113
	v_cvt_pk_bf16_f32 v187, v114, v115
	v_pk_mul_f32 v[110:111], v[110:111], v[118:119]
	v_pk_mul_f32 v[108:109], v[108:109], v[116:117]
	v_lshl_add_u64 v[84:85], s[20:21], 0, v[120:121]
	ds_read_b128 v[96:99], v96
	ds_write_b64 v182, v[186:187]
	v_cvt_pk_bf16_f32 v186, v108, v109
	v_cvt_pk_bf16_f32 v187, v110, v111
	v_pk_mul_f32 v[106:107], v[106:107], v[118:119]
	v_pk_mul_f32 v[104:105], v[104:105], v[116:117]
	v_pk_mul_f32 v[102:103], v[102:103], v[118:119]
	v_pk_mul_f32 v[100:101], v[100:101], v[116:117]
	global_load_dwordx4 v[80:83], v[76:77], off nt
	v_lshl_add_u64 v[88:89], v[146:147], 0, s[34:35]
	global_load_dwordx4 v[76:79], v120, s[20:21] nt
	v_add_co_u32_e64 v84, s[20:21], s60, v84
	s_lshl_b32 s34, s48, 10
	ds_write_b64 v182, v[186:187] offset:4352
	v_cvt_pk_bf16_f32 v186, v104, v105
	v_cvt_pk_bf16_f32 v187, v106, v107
	v_cvt_pk_bf16_f32 v116, v100, v101
	v_cvt_pk_bf16_f32 v117, v102, v103
	v_addc_co_u32_e64 v85, s[20:21], 0, v85, s[20:21]
	v_lshl_add_u64 v[92:93], v[148:149], 0, s[34:35]
	ds_write_b64 v182, v[186:187] offset:8704
	ds_write_b64 v182, v[116:117] offset:13056
	global_load_dwordx4 v[84:87], v[84:85], off nt
	v_add_u32_e32 v185, s31, v162
	global_load_dwordx4 v[88:91], v[88:89], off nt
	v_add_u32_e32 v194, s45, v159
	global_load_dwordx4 v[92:95], v[92:93], off
	s_waitcnt lgkmcnt(0)
	s_barrier
	ds_read_b128 v[218:221], v170 offset:17408
	ds_read_b128 v[222:225], v171
	ds_read_b128 v[226:229], v172
	ds_read_b128 v[230:233], v170 offset:17472
	ds_read_b128 v[234:237], v171 offset:64
	ds_read_b128 v[238:241], v172 offset:64
	ds_read_b128 v[242:245], v170 offset:17536
	ds_read_b128 v[246:249], v171 offset:128
	ds_read_b128 v[250:253], v172 offset:128
	s_add_i32 s34, s44, 1
	s_and_b64 s[20:21], exec, s[38:39]
	s_cselect_b32 s20, s34, s47
	s_lshl_b32 s34, s20, 6
	s_add_i32 s47, s47, -2
	v_lshl_add_u64 v[152:153], v[152:153], 0, s[36:37]
	s_waitcnt lgkmcnt(6)
	v_mfma_f32_16x16x32_bf16 v[190:193], v[218:221], v[222:225], 0
	v_mfma_f32_16x16x32_bf16 v[194:197], v[218:221], v[226:229], 0
	ds_read_b128 v[218:221], v170 offset:17600
	ds_read_b128 v[222:225], v171 offset:192
	ds_read_b128 v[226:229], v172 offset:192
	s_waitcnt lgkmcnt(6)
	v_mfma_f32_16x16x32_bf16 v[190:193], v[230:233], v[234:237], v[190:193]
	v_mfma_f32_16x16x32_bf16 v[194:197], v[230:233], v[238:241], v[194:197]
	ds_read_b64_tr_b16 v[230:231], v207
	ds_read_b64_tr_b16 v[232:233], v207 offset:576
	ds_read_b128 v[234:237], v210
	ds_read_b128 v[238:241], v211
	s_waitcnt lgkmcnt(7)
	v_mfma_f32_16x16x32_bf16 v[190:193], v[242:245], v[246:249], v[190:193]
	v_mfma_f32_16x16x32_bf16 v[194:197], v[242:245], v[250:253], v[194:197]
	ds_read_b64_tr_b16 v[242:243], v207 offset:4608
	ds_read_b64_tr_b16 v[244:245], v207 offset:5184
	ds_read_b128 v[246:249], v210 offset:64
	ds_read_b128 v[250:253], v211 offset:64
	s_waitcnt lgkmcnt(8)
	v_mfma_f32_16x16x32_bf16 v[190:193], v[218:221], v[222:225], v[190:193]
	v_mfma_f32_16x16x32_bf16 v[194:197], v[218:221], v[226:229], v[194:197]
	ds_read_b128 v[218:221], v183
	ds_read_b128 v[222:225], v171 offset:44032
	ds_read_b128 v[226:229], v172 offset:44032
	s_waitcnt lgkmcnt(7)
	v_mfma_f32_16x16x32_bf16 v[198:201], v[230:233], v[234:237], 0
	v_mfma_f32_16x16x32_bf16 v[202:205], v[230:233], v[238:241], 0
	ds_read_b128 v[230:233], v183 offset:64
	ds_read_b128 v[234:237], v171 offset:44096
	ds_read_b128 v[238:241], v172 offset:44096
	s_waitcnt lgkmcnt(6)
	v_mfma_f32_16x16x32_bf16 v[198:201], v[242:245], v[246:249], v[198:201]
	v_mfma_f32_16x16x32_bf16 v[202:205], v[242:245], v[250:253], v[202:205]
	ds_read_b128 v[242:245], v183 offset:128
	ds_read_b128 v[246:249], v171 offset:44160
	ds_read_b128 v[250:253], v172 offset:44160
	v_cndmask_b32_e32 v190, 0, v190, vcc
	v_cndmask_b32_e64 v191, 0, v191, s[6:7]
	v_cndmask_b32_e64 v192, 0, v192, s[8:9]
	v_cndmask_b32_e64 v193, 0, v193, s[10:11]
	v_cvt_pk_bf16_f32 v190, v190, v191
	v_cvt_pk_bf16_f32 v191, v192, v193
	v_cndmask_b32_e64 v194, 0, v194, s[12:13]
	v_cndmask_b32_e64 v195, 0, v195, s[14:15]
	v_cndmask_b32_e64 v196, 0, v196, s[16:17]
	v_cndmask_b32_e64 v197, 0, v197, s[18:19]
	v_cvt_pk_bf16_f32 v194, v194, v195
	v_cvt_pk_bf16_f32 v195, v196, v197
	ds_write_b64 v175, v[190:191]
	ds_write_b64 v177, v[194:195]
	s_waitcnt lgkmcnt(8)
	v_mfma_f32_16x16x32_bf16 v[198:201], v[218:221], v[222:225], v[198:201]
	v_mfma_f32_16x16x32_bf16 v[202:205], v[218:221], v[226:229], v[202:205]
	ds_read_b64_tr_b16 v[190:191], v178 offset:61440
	ds_read_b64_tr_b16 v[192:193], v178 offset:62528
	ds_read_b64_tr_b16 v[194:195], v181 offset:8704
	ds_read_b64_tr_b16 v[196:197], v181 offset:9792
	s_waitcnt lgkmcnt(9)
	v_mfma_f32_16x16x32_bf16 v[198:201], v[230:233], v[234:237], v[198:201]
	v_mfma_f32_16x16x32_bf16 v[202:205], v[230:233], v[238:241], v[202:205]
	ds_read_b128 v[230:233], v183 offset:192
	ds_read_b128 v[234:237], v171 offset:44224
	ds_read_b128 v[238:241], v172 offset:44224
	s_waitcnt lgkmcnt(9)
	v_mfma_f32_16x16x32_bf16 v[198:201], v[242:245], v[246:249], v[198:201]
	v_mfma_f32_16x16x32_bf16 v[202:205], v[242:245], v[250:253], v[202:205]
	ds_read_b64_tr_b16 v[242:243], v162
	ds_read_b64_tr_b16 v[244:245], v162 offset:576
	ds_read_b64_tr_b16 v[246:247], v162 offset:32
	ds_read_b64_tr_b16 v[248:249], v162 offset:608
	s_waitcnt lgkmcnt(7)
	ds_read_b64_tr_b16 v[218:219], v162 offset:64
	ds_read_b64_tr_b16 v[220:221], v162 offset:640
	ds_read_b64_tr_b16 v[222:223], v162 offset:96
	ds_read_b64_tr_b16 v[224:225], v162 offset:672
	s_waitcnt lgkmcnt(8)
	v_mfma_f32_16x16x32_bf16 v[198:201], v[230:233], v[234:237], v[198:201]
	v_mfma_f32_16x16x32_bf16 v[202:205], v[230:233], v[238:241], v[202:205]
	ds_read_b64_tr_b16 v[230:231], v162 offset:4608
	ds_read_b64_tr_b16 v[232:233], v162 offset:5184
	ds_read_b64_tr_b16 v[234:235], v162 offset:4640
	ds_read_b64_tr_b16 v[236:237], v162 offset:5216
	s_waitcnt lgkmcnt(8)
	v_mfma_f32_16x16x32_bf16 v[112:115], v[190:193], v[242:245], v[112:115]
	v_mfma_f32_16x16x32_bf16 v[108:111], v[190:193], v[246:249], v[108:111]
	ds_read_b64_tr_b16 v[242:243], v162 offset:4672
	ds_read_b64_tr_b16 v[244:245], v162 offset:5248
	ds_read_b64_tr_b16 v[246:247], v162 offset:4704
	ds_read_b64_tr_b16 v[248:249], v162 offset:5280
	v_cvt_pk_bf16_f32 v198, v198, v199
	v_cvt_pk_bf16_f32 v199, v200, v201
	v_add_u32_e32 v254, s34, v173
	v_mad_u64_u32 v[254:255], s[20:21], v254, s42, 0
	v_lshl_add_u64 v[254:255], v[254:255], 1, v[150:151]
	v_cvt_pk_bf16_f32 v202, v202, v203
	v_cvt_pk_bf16_f32 v203, v204, v205
	global_store_dwordx2 v[254:255], v[198:199], off
	v_add_u32_e32 v254, s34, v179
	v_mad_u64_u32 v[254:255], s[20:21], v254, s42, 0
	v_lshl_add_u64 v[254:255], v[254:255], 1, v[150:151]
	global_store_dwordx2 v[254:255], v[202:203], off
	s_waitcnt lgkmcnt(8)
	v_mfma_f32_16x16x32_bf16 v[214:217], v[190:193], v[218:221], v[104:107]
	v_mfma_f32_16x16x32_bf16 v[116:119], v[190:193], v[222:225], v[100:103]
	s_waitcnt lgkmcnt(4)
	v_mfma_f32_16x16x32_bf16 v[100:103], v[194:197], v[230:233], v[112:115]
	v_mfma_f32_16x16x32_bf16 v[104:107], v[194:197], v[234:237], v[108:111]
	s_waitcnt lgkmcnt(0)
	v_mfma_f32_16x16x32_bf16 v[108:111], v[194:197], v[242:245], v[214:217]
	v_mfma_f32_16x16x32_bf16 v[112:115], v[194:197], v[246:249], v[116:119]
	s_add_i32 s20, s44, 2
	s_cmp_lt_u32 s44, 62
	s_mov_b32 s44, s20
	s_waitcnt lgkmcnt(0)
	s_barrier
	s_cbranch_scc1 .LBB0_350
	s_add_i32 s30, s30, s28
	v_lshl_add_u64 v[140:141], v[140:141], 0, s[26:27]
	s_cmpk_lt_i32 s30, 0x100
	v_add_u32_e32 v165, s29, v165
	s_cbranch_scc1 .LBB0_344
